# v58 + prep pool-weight fold on f32 matrix cores: v_mfma_f32_16x16x4_f32 (f32 operands, f32 accumulate, k-ordered = same fmaf chain) replaces 1024 v_readlane + 512 v_pk_fma per wave item; 16 rows x 32
# speedup vs baseline: 1.0121x; 1.0022x over previous
.LBB0_66:
	s_ashr_i32 s6, s83, 10
	s_lshr_b32 s4, s83, 5
	s_and_b32 s4, s4, 31
	s_lshl_b32 s4, s4, 4
	s_and_b32 s5, s83, 31
	s_lshl_b32 s5, s5, 5
	s_and_b32 s7, s4, 0x180
	s_lshl_b32 s8, s6, 9
	s_add_i32 s9, s8, s4
	s_add_i32 s12, s8, s7
	v_and_b32_e32 v56, 15, v223
	v_lshrrev_b32_e32 v57, 4, v223
	v_add_u32_e32 v58, s9, v56
	v_lshlrev_b32_e32 v58, 9, v58
	v_lshl_add_u32 v58, v57, 2, v58
	v_lshlrev_b32_e32 v59, 2, v57
	v_lshlrev_b32_e32 v124, 12, v57
	v_lshl_add_u32 v124, v56, 2, v124
	v_readlane_b32 s10, v251, 37
	v_readlane_b32 s11, v251, 38
	v_readlane_b32 s14, v251, 39
	v_readlane_b32 s15, v251, 40
	v_readlane_b32 s16, v251, 43
	v_readlane_b32 s17, v251, 44
	v_readlane_b32 s70, v251, 31
	v_readlane_b32 s71, v251, 32
	s_mov_b64 s[20:21], s[10:11]
	s_lshl_b32 s13, s12, 2
	s_add_u32 s22, s14, s13
	s_addc_u32 s23, s15, 0
	s_lshl_b32 s13, s12, 12
	s_add_u32 s24, s16, s13
	s_addc_u32 s25, s17, 0
	s_lshl_b32 s13, s5, 2
	s_add_u32 s24, s24, s13
	s_addc_u32 s25, s25, 0
	global_load_dword v60, v58, s[20:21]
	global_load_dword v61, v58, s[20:21] offset:16
	global_load_dword v62, v58, s[20:21] offset:32
	global_load_dword v63, v58, s[20:21] offset:48
	global_load_dword v64, v58, s[20:21] offset:64
	global_load_dword v65, v58, s[20:21] offset:80
	global_load_dword v66, v58, s[20:21] offset:96
	global_load_dword v67, v58, s[20:21] offset:112
	global_load_dword v68, v58, s[20:21] offset:128
	global_load_dword v69, v58, s[20:21] offset:144
	global_load_dword v70, v58, s[20:21] offset:160
	global_load_dword v71, v58, s[20:21] offset:176
	global_load_dword v72, v58, s[20:21] offset:192
	global_load_dword v73, v58, s[20:21] offset:208
	global_load_dword v74, v58, s[20:21] offset:224
	global_load_dword v75, v58, s[20:21] offset:240
	global_load_dword v76, v58, s[20:21] offset:256
	global_load_dword v77, v58, s[20:21] offset:272
	global_load_dword v78, v58, s[20:21] offset:288
	global_load_dword v79, v58, s[20:21] offset:304
	global_load_dword v80, v58, s[20:21] offset:320
	global_load_dword v81, v58, s[20:21] offset:336
	global_load_dword v82, v58, s[20:21] offset:352
	global_load_dword v83, v58, s[20:21] offset:368
	global_load_dword v84, v58, s[20:21] offset:384
	global_load_dword v85, v58, s[20:21] offset:400
	global_load_dword v86, v58, s[20:21] offset:416
	global_load_dword v87, v58, s[20:21] offset:432
	global_load_dword v88, v58, s[20:21] offset:448
	global_load_dword v89, v58, s[20:21] offset:464
	global_load_dword v90, v58, s[20:21] offset:480
	global_load_dword v91, v58, s[20:21] offset:496
	global_load_dword v92, v59, s[22:23]
	global_load_dword v93, v59, s[22:23] offset:16
	global_load_dword v94, v59, s[22:23] offset:32
	global_load_dword v95, v59, s[22:23] offset:48
	global_load_dword v96, v59, s[22:23] offset:64
	global_load_dword v97, v59, s[22:23] offset:80
	global_load_dword v98, v59, s[22:23] offset:96
	global_load_dword v99, v59, s[22:23] offset:112
	global_load_dword v100, v59, s[22:23] offset:128
	global_load_dword v101, v59, s[22:23] offset:144
	global_load_dword v102, v59, s[22:23] offset:160
	global_load_dword v103, v59, s[22:23] offset:176
	global_load_dword v104, v59, s[22:23] offset:192
	global_load_dword v105, v59, s[22:23] offset:208
	global_load_dword v106, v59, s[22:23] offset:224
	global_load_dword v107, v59, s[22:23] offset:240
	global_load_dword v126, v124, s[24:25]
	global_load_dword v127, v124, s[24:25] offset:64
	s_add_u32 s24, s24, 0x4000
	s_addc_u32 s25, s25, 0
	global_load_dword v128, v124, s[24:25]
	global_load_dword v129, v124, s[24:25] offset:64
	s_add_u32 s24, s24, 0x4000
	s_addc_u32 s25, s25, 0
	global_load_dword v130, v124, s[24:25]
	global_load_dword v131, v124, s[24:25] offset:64
	s_add_u32 s24, s24, 0x4000
	s_addc_u32 s25, s25, 0
	global_load_dword v132, v124, s[24:25]
	global_load_dword v133, v124, s[24:25] offset:64
	s_add_u32 s24, s24, 0x4000
	s_addc_u32 s25, s25, 0
	global_load_dword v134, v124, s[24:25]
	global_load_dword v135, v124, s[24:25] offset:64
	s_add_u32 s24, s24, 0x4000
	s_addc_u32 s25, s25, 0
	global_load_dword v136, v124, s[24:25]
	global_load_dword v137, v124, s[24:25] offset:64
	s_add_u32 s24, s24, 0x4000
	s_addc_u32 s25, s25, 0
	s_waitcnt vmcnt(12)
	v_mul_f32_e32 v60, v60, v92
	v_mul_f32_e32 v61, v61, v93
	v_mul_f32_e32 v62, v62, v94
	v_mul_f32_e32 v63, v63, v95
	v_mul_f32_e32 v64, v64, v96
	v_mul_f32_e32 v65, v65, v97
	v_mul_f32_e32 v66, v66, v98
	v_mul_f32_e32 v67, v67, v99
	v_mul_f32_e32 v68, v68, v100
	v_mul_f32_e32 v69, v69, v101
	v_mul_f32_e32 v70, v70, v102
	v_mul_f32_e32 v71, v71, v103
	v_mul_f32_e32 v72, v72, v104
	v_mul_f32_e32 v73, v73, v105
	v_mul_f32_e32 v74, v74, v106
	v_mul_f32_e32 v75, v75, v107
	global_load_dword v108, v59, s[22:23] offset:256
	global_load_dword v109, v59, s[22:23] offset:272
	global_load_dword v110, v59, s[22:23] offset:288
	global_load_dword v111, v59, s[22:23] offset:304
	global_load_dword v112, v59, s[22:23] offset:320
	global_load_dword v113, v59, s[22:23] offset:336
	global_load_dword v114, v59, s[22:23] offset:352
	global_load_dword v115, v59, s[22:23] offset:368
	global_load_dword v116, v59, s[22:23] offset:384
	global_load_dword v117, v59, s[22:23] offset:400
	global_load_dword v118, v59, s[22:23] offset:416
	global_load_dword v119, v59, s[22:23] offset:432
	global_load_dword v120, v59, s[22:23] offset:448
	global_load_dword v121, v59, s[22:23] offset:464
	global_load_dword v122, v59, s[22:23] offset:480
	global_load_dword v123, v59, s[22:23] offset:496
	global_load_dword v138, v124, s[24:25]
	global_load_dword v139, v124, s[24:25] offset:64
	s_add_u32 s24, s24, 0x4000
	s_addc_u32 s25, s25, 0
	global_load_dword v140, v124, s[24:25]
	global_load_dword v141, v124, s[24:25] offset:64
	s_add_u32 s24, s24, 0x4000
	s_addc_u32 s25, s25, 0
	global_load_dword v142, v124, s[24:25]
	global_load_dword v143, v124, s[24:25] offset:64
	s_add_u32 s24, s24, 0x4000
	s_addc_u32 s25, s25, 0
	global_load_dword v144, v124, s[24:25]
	global_load_dword v145, v124, s[24:25] offset:64
	s_add_u32 s24, s24, 0x4000
	s_addc_u32 s25, s25, 0
	global_load_dword v146, v124, s[24:25]
	global_load_dword v147, v124, s[24:25] offset:64
	s_add_u32 s24, s24, 0x4000
	s_addc_u32 s25, s25, 0
	global_load_dword v148, v124, s[24:25]
	global_load_dword v149, v124, s[24:25] offset:64
	s_add_u32 s24, s24, 0x4000
	s_addc_u32 s25, s25, 0
	global_load_dword v150, v124, s[24:25]
	global_load_dword v151, v124, s[24:25] offset:64
	s_add_u32 s24, s24, 0x4000
	s_addc_u32 s25, s25, 0
	global_load_dword v152, v124, s[24:25]
	global_load_dword v153, v124, s[24:25] offset:64
	s_add_u32 s24, s24, 0x4000
	s_addc_u32 s25, s25, 0
	global_load_dword v154, v124, s[24:25]
	global_load_dword v155, v124, s[24:25] offset:64
	s_add_u32 s24, s24, 0x4000
	s_addc_u32 s25, s25, 0
	global_load_dword v156, v124, s[24:25]
	global_load_dword v157, v124, s[24:25] offset:64
	s_add_u32 s24, s24, 0x4000
	s_addc_u32 s25, s25, 0
	s_waitcnt vmcnt(20)
	v_mul_f32_e32 v76, v76, v108
	v_mul_f32_e32 v77, v77, v109
	v_mul_f32_e32 v78, v78, v110
	v_mul_f32_e32 v79, v79, v111
	v_mul_f32_e32 v80, v80, v112
	v_mul_f32_e32 v81, v81, v113
	v_mul_f32_e32 v82, v82, v114
	v_mul_f32_e32 v83, v83, v115
	v_mul_f32_e32 v84, v84, v116
	v_mul_f32_e32 v85, v85, v117
	v_mul_f32_e32 v86, v86, v118
	v_mul_f32_e32 v87, v87, v119
	v_mul_f32_e32 v88, v88, v120
	v_mul_f32_e32 v89, v89, v121
	v_mul_f32_e32 v90, v90, v122
	v_mul_f32_e32 v91, v91, v123
	s_nop 1
	s_waitcnt vmcnt(30)
	v_mfma_f32_16x16x4_f32 v[160:163], v60, v126, 0
	v_mfma_f32_16x16x4_f32 v[164:167], v60, v127, 0
	global_load_dword v126, v124, s[24:25]
	global_load_dword v127, v124, s[24:25] offset:64
	s_add_u32 s24, s24, 0x4000
	s_addc_u32 s25, s25, 0
	s_waitcnt vmcnt(30)
	v_mfma_f32_16x16x4_f32 v[160:163], v61, v128, v[160:163]
	v_mfma_f32_16x16x4_f32 v[164:167], v61, v129, v[164:167]
	global_load_dword v128, v124, s[24:25]
	global_load_dword v129, v124, s[24:25] offset:64
	s_add_u32 s24, s24, 0x4000
	s_addc_u32 s25, s25, 0
	s_waitcnt vmcnt(30)
	v_mfma_f32_16x16x4_f32 v[160:163], v62, v130, v[160:163]
	v_mfma_f32_16x16x4_f32 v[164:167], v62, v131, v[164:167]
	global_load_dword v130, v124, s[24:25]
	global_load_dword v131, v124, s[24:25] offset:64
	s_add_u32 s24, s24, 0x4000
	s_addc_u32 s25, s25, 0
	s_waitcnt vmcnt(30)
	v_mfma_f32_16x16x4_f32 v[160:163], v63, v132, v[160:163]
	v_mfma_f32_16x16x4_f32 v[164:167], v63, v133, v[164:167]
	global_load_dword v132, v124, s[24:25]
	global_load_dword v133, v124, s[24:25] offset:64
	s_add_u32 s24, s24, 0x4000
	s_addc_u32 s25, s25, 0
	s_waitcnt vmcnt(30)
	v_mfma_f32_16x16x4_f32 v[160:163], v64, v134, v[160:163]
	v_mfma_f32_16x16x4_f32 v[164:167], v64, v135, v[164:167]
	global_load_dword v134, v124, s[24:25]
	global_load_dword v135, v124, s[24:25] offset:64
	s_add_u32 s24, s24, 0x4000
	s_addc_u32 s25, s25, 0
	s_waitcnt vmcnt(30)
	v_mfma_f32_16x16x4_f32 v[160:163], v65, v136, v[160:163]
	v_mfma_f32_16x16x4_f32 v[164:167], v65, v137, v[164:167]
	global_load_dword v136, v124, s[24:25]
	global_load_dword v137, v124, s[24:25] offset:64
	s_add_u32 s24, s24, 0x4000
	s_addc_u32 s25, s25, 0
	s_waitcnt vmcnt(30)
	v_mfma_f32_16x16x4_f32 v[160:163], v66, v138, v[160:163]
	v_mfma_f32_16x16x4_f32 v[164:167], v66, v139, v[164:167]
	global_load_dword v138, v124, s[24:25]
	global_load_dword v139, v124, s[24:25] offset:64
	s_add_u32 s24, s24, 0x4000
	s_addc_u32 s25, s25, 0
	s_waitcnt vmcnt(30)
	v_mfma_f32_16x16x4_f32 v[160:163], v67, v140, v[160:163]
	v_mfma_f32_16x16x4_f32 v[164:167], v67, v141, v[164:167]
	global_load_dword v140, v124, s[24:25]
	global_load_dword v141, v124, s[24:25] offset:64
	s_add_u32 s24, s24, 0x4000
	s_addc_u32 s25, s25, 0
	s_waitcnt vmcnt(30)
	v_mfma_f32_16x16x4_f32 v[160:163], v68, v142, v[160:163]
	v_mfma_f32_16x16x4_f32 v[164:167], v68, v143, v[164:167]
	global_load_dword v142, v124, s[24:25]
	global_load_dword v143, v124, s[24:25] offset:64
	s_add_u32 s24, s24, 0x4000
	s_addc_u32 s25, s25, 0
	s_waitcnt vmcnt(30)
	v_mfma_f32_16x16x4_f32 v[160:163], v69, v144, v[160:163]
	v_mfma_f32_16x16x4_f32 v[164:167], v69, v145, v[164:167]
	global_load_dword v144, v124, s[24:25]
	global_load_dword v145, v124, s[24:25] offset:64
	s_add_u32 s24, s24, 0x4000
	s_addc_u32 s25, s25, 0
	s_waitcnt vmcnt(30)
	v_mfma_f32_16x16x4_f32 v[160:163], v70, v146, v[160:163]
	v_mfma_f32_16x16x4_f32 v[164:167], v70, v147, v[164:167]
	global_load_dword v146, v124, s[24:25]
	global_load_dword v147, v124, s[24:25] offset:64
	s_add_u32 s24, s24, 0x4000
	s_addc_u32 s25, s25, 0
	s_waitcnt vmcnt(30)
	v_mfma_f32_16x16x4_f32 v[160:163], v71, v148, v[160:163]
	v_mfma_f32_16x16x4_f32 v[164:167], v71, v149, v[164:167]
	global_load_dword v148, v124, s[24:25]
	global_load_dword v149, v124, s[24:25] offset:64
	s_add_u32 s24, s24, 0x4000
	s_addc_u32 s25, s25, 0
	s_waitcnt vmcnt(30)
	v_mfma_f32_16x16x4_f32 v[160:163], v72, v150, v[160:163]
	v_mfma_f32_16x16x4_f32 v[164:167], v72, v151, v[164:167]
	global_load_dword v150, v124, s[24:25]
	global_load_dword v151, v124, s[24:25] offset:64
	s_add_u32 s24, s24, 0x4000
	s_addc_u32 s25, s25, 0
	s_waitcnt vmcnt(30)
	v_mfma_f32_16x16x4_f32 v[160:163], v73, v152, v[160:163]
	v_mfma_f32_16x16x4_f32 v[164:167], v73, v153, v[164:167]
	global_load_dword v152, v124, s[24:25]
	global_load_dword v153, v124, s[24:25] offset:64
	s_add_u32 s24, s24, 0x4000
	s_addc_u32 s25, s25, 0
	s_waitcnt vmcnt(30)
	v_mfma_f32_16x16x4_f32 v[160:163], v74, v154, v[160:163]
	v_mfma_f32_16x16x4_f32 v[164:167], v74, v155, v[164:167]
	global_load_dword v154, v124, s[24:25]
	global_load_dword v155, v124, s[24:25] offset:64
	s_add_u32 s24, s24, 0x4000
	s_addc_u32 s25, s25, 0
	s_waitcnt vmcnt(30)
	v_mfma_f32_16x16x4_f32 v[160:163], v75, v156, v[160:163]
	v_mfma_f32_16x16x4_f32 v[164:167], v75, v157, v[164:167]
	global_load_dword v156, v124, s[24:25]
	global_load_dword v157, v124, s[24:25] offset:64
	s_add_u32 s24, s24, 0x4000
	s_addc_u32 s25, s25, 0
	s_waitcnt vmcnt(30)
	v_mfma_f32_16x16x4_f32 v[160:163], v76, v126, v[160:163]
	v_mfma_f32_16x16x4_f32 v[164:167], v76, v127, v[164:167]
	s_waitcnt vmcnt(28)
	v_mfma_f32_16x16x4_f32 v[160:163], v77, v128, v[160:163]
	v_mfma_f32_16x16x4_f32 v[164:167], v77, v129, v[164:167]
	s_waitcnt vmcnt(26)
	v_mfma_f32_16x16x4_f32 v[160:163], v78, v130, v[160:163]
	v_mfma_f32_16x16x4_f32 v[164:167], v78, v131, v[164:167]
	s_waitcnt vmcnt(24)
	v_mfma_f32_16x16x4_f32 v[160:163], v79, v132, v[160:163]
	v_mfma_f32_16x16x4_f32 v[164:167], v79, v133, v[164:167]
	s_waitcnt vmcnt(22)
	v_mfma_f32_16x16x4_f32 v[160:163], v80, v134, v[160:163]
	v_mfma_f32_16x16x4_f32 v[164:167], v80, v135, v[164:167]
	s_waitcnt vmcnt(20)
	v_mfma_f32_16x16x4_f32 v[160:163], v81, v136, v[160:163]
	v_mfma_f32_16x16x4_f32 v[164:167], v81, v137, v[164:167]
	s_waitcnt vmcnt(18)
	v_mfma_f32_16x16x4_f32 v[160:163], v82, v138, v[160:163]
	v_mfma_f32_16x16x4_f32 v[164:167], v82, v139, v[164:167]
	s_waitcnt vmcnt(16)
	v_mfma_f32_16x16x4_f32 v[160:163], v83, v140, v[160:163]
	v_mfma_f32_16x16x4_f32 v[164:167], v83, v141, v[164:167]
	s_waitcnt vmcnt(14)
	v_mfma_f32_16x16x4_f32 v[160:163], v84, v142, v[160:163]
	v_mfma_f32_16x16x4_f32 v[164:167], v84, v143, v[164:167]
	s_waitcnt vmcnt(12)
	v_mfma_f32_16x16x4_f32 v[160:163], v85, v144, v[160:163]
	v_mfma_f32_16x16x4_f32 v[164:167], v85, v145, v[164:167]
	s_waitcnt vmcnt(10)
	v_mfma_f32_16x16x4_f32 v[160:163], v86, v146, v[160:163]
	v_mfma_f32_16x16x4_f32 v[164:167], v86, v147, v[164:167]
	s_waitcnt vmcnt(8)
	v_mfma_f32_16x16x4_f32 v[160:163], v87, v148, v[160:163]
	v_mfma_f32_16x16x4_f32 v[164:167], v87, v149, v[164:167]
	s_waitcnt vmcnt(6)
	v_mfma_f32_16x16x4_f32 v[160:163], v88, v150, v[160:163]
	v_mfma_f32_16x16x4_f32 v[164:167], v88, v151, v[164:167]
	s_waitcnt vmcnt(4)
	v_mfma_f32_16x16x4_f32 v[160:163], v89, v152, v[160:163]
	v_mfma_f32_16x16x4_f32 v[164:167], v89, v153, v[164:167]
	s_waitcnt vmcnt(2)
	v_mfma_f32_16x16x4_f32 v[160:163], v90, v154, v[160:163]
	v_mfma_f32_16x16x4_f32 v[164:167], v90, v155, v[164:167]
	s_waitcnt vmcnt(0)
	v_mfma_f32_16x16x4_f32 v[160:163], v91, v156, v[160:163]
	v_mfma_f32_16x16x4_f32 v[164:167], v91, v157, v[164:167]
	s_mul_hi_i32 s7, s6, 0x2b80000
	s_mul_i32 s6, s6, 0x2b80000
	s_add_u32 s26, s70, s6
	s_addc_u32 s27, s71, s7
	s_add_u32 s26, s26, 0x1c00000
	s_addc_u32 s27, s27, 0
	s_lshl_b32 s13, s5, 10
	s_add_u32 s26, s26, s13
	s_addc_u32 s27, s27, 0
	s_lshl_b32 s13, s4, 1
	s_add_u32 s26, s26, s13
	s_addc_u32 s27, s27, 0
	v_lshlrev_b32_e32 v172, 10, v56
	v_lshl_add_u32 v172, v57, 3, v172
	v_add_u32_e32 v173, 0x4000, v172
	s_nop 7
	s_nop 7
	v_cvt_pk_bf16_f32 v168, v160, v161
	v_cvt_pk_bf16_f32 v169, v162, v163
	v_cvt_pk_bf16_f32 v170, v164, v165
	v_cvt_pk_bf16_f32 v171, v166, v167
	s_add_i32 s83, s83, s89
	s_add_i32 s80, s80, s3
	s_mov_b32 s72, s89
	global_store_dwordx2 v172, v[168:169], s[26:27]
	global_store_dwordx2 v173, v[170:171], s[26:27]
	s_cmpk_gt_i32 s83, 0x7ff
	s_cbranch_scc0 .LBB0_66
